# final norm hand-written like norm1/norm2; phase-0 modulation GEMV item: silu inputs and all 32 weight rows issued together
# speedup vs baseline: 1.0138x; 1.0047x over previous
.LBB0_20:
	s_and_b64 vcc, exec, s[30:31]
	s_cbranch_vccz .LBB0_12
	v_readlane_b32 s4, v237, 57
	v_readlane_b32 s63, v237, 0
	v_readlane_b32 s5, v237, 58
	s_load_dword s61, s[4:5], 0x0
	s_mov_b64 s[38:39], -1
	s_mov_b64 s[30:31], 0
	s_mov_b64 s[36:37], 0
	s_waitcnt lgkmcnt(0)
	s_lshl_b32 s34, s61, 3
	s_cmp_lt_i32 s64, 21
	s_cbranch_scc1 .LBB0_32
	s_cmp_eq_u32 s64, 21
	s_mov_b64 s[36:37], -1
	s_cbranch_scc0 .LBB0_31
	s_branch .Lnm2_entry

.Lnm2_entry:
	v_and_b32_e32 v134, 63, v206
	v_lshrrev_b32_e32 v135, 6, v206
	v_lshlrev_b32_e32 v132, 4, v134
	v_readfirstlane_b32 s40, v135
	s_lshl_b32 s41, s63, 3
	s_add_u32 s41, s41, s40
	s_add_u32 s44, s96, 0x9484000
	s_addc_u32 s45, s97, 0
	s_add_u32 s46, s44, 0x1000000
	s_addc_u32 s47, s45, 0
	s_lshl_b32 s42, s41, 12
	s_add_u32 s48, s44, s42
	s_addc_u32 s49, s45, 0
	s_add_u32 s50, s48, 0x800000
	s_addc_u32 s51, s49, 0
	s_add_u32 s52, s46, s42
	s_addc_u32 s53, s47, 0
	global_load_dwordx4 v[4:7], v132, s[48:49]
	global_load_dwordx4 v[8:11], v132, s[48:49] offset:1024
	global_load_dwordx4 v[12:15], v132, s[48:49] offset:2048
	global_load_dwordx4 v[16:19], v132, s[48:49] offset:3072
	global_load_dwordx4 v[20:23], v132, s[50:51]
	global_load_dwordx4 v[24:27], v132, s[50:51] offset:1024
	global_load_dwordx4 v[28:31], v132, s[50:51] offset:2048
	global_load_dwordx4 v[32:35], v132, s[50:51] offset:3072
	global_load_dwordx4 v[36:39], v132, s[52:53]
	global_load_dwordx4 v[40:43], v132, s[52:53] offset:1024
	global_load_dwordx4 v[44:47], v132, s[52:53] offset:2048
	global_load_dwordx4 v[48:51], v132, s[52:53] offset:3072
	v_readlane_b32 s54, v237, 5
	v_readlane_b32 s55, v237, 6
	s_nop 4
	global_load_dwordx4 v[52:55], v132, s[54:55]
	global_load_dwordx4 v[56:59], v132, s[54:55] offset:1024
	global_load_dwordx4 v[60:63], v132, s[54:55] offset:2048
	global_load_dwordx4 v[64:67], v132, s[54:55] offset:3072
	v_readlane_b32 s48, v237, 7
	v_readlane_b32 s49, v237, 8
	s_lshl_b32 s42, s41, 12
	s_add_u32 s48, s48, s42
	s_addc_u32 s49, s49, 0
	s_waitcnt vmcnt(12)
	v_mul_f32_e32 v133, v4, v4
	v_fmac_f32_e32 v133, v5, v5
	v_fmac_f32_e32 v133, v6, v6
	v_fmac_f32_e32 v133, v7, v7
	v_fmac_f32_e32 v133, v8, v8
	v_fmac_f32_e32 v133, v9, v9
	v_fmac_f32_e32 v133, v10, v10
	v_fmac_f32_e32 v133, v11, v11
	v_fmac_f32_e32 v133, v12, v12
	v_fmac_f32_e32 v133, v13, v13
	v_fmac_f32_e32 v133, v14, v14
	v_fmac_f32_e32 v133, v15, v15
	v_fmac_f32_e32 v133, v16, v16
	v_fmac_f32_e32 v133, v17, v17
	v_fmac_f32_e32 v133, v18, v18
	v_fmac_f32_e32 v133, v19, v19
	s_nop 1
	v_add_f32_dpp v133, v133, v133 row_shr:1 row_mask:0xf bank_mask:0xf bound_ctrl:0
	s_nop 1
	v_add_f32_dpp v133, v133, v133 row_shr:2 row_mask:0xf bank_mask:0xf bound_ctrl:0
	s_nop 1
	v_add_f32_dpp v133, v133, v133 row_shr:4 row_mask:0xf bank_mask:0xf bound_ctrl:0
	s_nop 1
	v_add_f32_dpp v133, v133, v133 row_shr:8 row_mask:0xf bank_mask:0xf bound_ctrl:0
	s_nop 1
	v_readlane_b32 s35, v133, 15
	v_readlane_b32 s42, v133, 31
	v_readlane_b32 s43, v133, 47
	v_readlane_b32 s54, v133, 63
	v_mov_b32_e32 v135, s35
	v_add_f32_e32 v135, s42, v135
	v_add_f32_e32 v135, s43, v135
	v_add_f32_e32 v135, s54, v135
	v_mov_b32_e32 v136, 0x358637bd
	v_fmac_f32_e32 v136, 0x3a800000, v135
	v_rsq_f32_e32 v136, v136
	s_nop 0
	s_waitcnt vmcnt(0)
	v_mul_f32_e32 v4, v4, v136
	v_mul_f32_e32 v4, v4, v52
	v_mul_f32_e32 v5, v5, v136
	v_mul_f32_e32 v5, v5, v53
	v_mul_f32_e32 v6, v6, v136
	v_mul_f32_e32 v6, v6, v54
	v_mul_f32_e32 v7, v7, v136
	v_mul_f32_e32 v7, v7, v55
	global_store_dwordx4 v132, v[4:7], s[48:49] offset:0
	v_mul_f32_e32 v8, v8, v136
	v_mul_f32_e32 v8, v8, v56
	v_mul_f32_e32 v9, v9, v136
	v_mul_f32_e32 v9, v9, v57
	v_mul_f32_e32 v10, v10, v136
	v_mul_f32_e32 v10, v10, v58
	v_mul_f32_e32 v11, v11, v136
	v_mul_f32_e32 v11, v11, v59
	global_store_dwordx4 v132, v[8:11], s[48:49] offset:1024
	v_mul_f32_e32 v12, v12, v136
	v_mul_f32_e32 v12, v12, v60
	v_mul_f32_e32 v13, v13, v136
	v_mul_f32_e32 v13, v13, v61
	v_mul_f32_e32 v14, v14, v136
	v_mul_f32_e32 v14, v14, v62
	v_mul_f32_e32 v15, v15, v136
	v_mul_f32_e32 v15, v15, v63
	global_store_dwordx4 v132, v[12:15], s[48:49] offset:2048
	v_mul_f32_e32 v16, v16, v136
	v_mul_f32_e32 v16, v16, v64
	v_mul_f32_e32 v17, v17, v136
	v_mul_f32_e32 v17, v17, v65
	v_mul_f32_e32 v18, v18, v136
	v_mul_f32_e32 v18, v18, v66
	v_mul_f32_e32 v19, v19, v136
	v_mul_f32_e32 v19, v19, v67
	global_store_dwordx4 v132, v[16:19], s[48:49] offset:3072
	s_add_u32 s48, s48, 0x800000
	s_addc_u32 s49, s49, 0
	s_waitcnt vmcnt(8)
	v_mul_f32_e32 v133, v20, v20
	v_fmac_f32_e32 v133, v21, v21
	v_fmac_f32_e32 v133, v22, v22
	v_fmac_f32_e32 v133, v23, v23
	v_fmac_f32_e32 v133, v24, v24
	v_fmac_f32_e32 v133, v25, v25
	v_fmac_f32_e32 v133, v26, v26
	v_fmac_f32_e32 v133, v27, v27
	v_fmac_f32_e32 v133, v28, v28
	v_fmac_f32_e32 v133, v29, v29
	v_fmac_f32_e32 v133, v30, v30
	v_fmac_f32_e32 v133, v31, v31
	v_fmac_f32_e32 v133, v32, v32
	v_fmac_f32_e32 v133, v33, v33
	v_fmac_f32_e32 v133, v34, v34
	v_fmac_f32_e32 v133, v35, v35
	s_nop 1
	v_add_f32_dpp v133, v133, v133 row_shr:1 row_mask:0xf bank_mask:0xf bound_ctrl:0
	s_nop 1
	v_add_f32_dpp v133, v133, v133 row_shr:2 row_mask:0xf bank_mask:0xf bound_ctrl:0
	s_nop 1
	v_add_f32_dpp v133, v133, v133 row_shr:4 row_mask:0xf bank_mask:0xf bound_ctrl:0
	s_nop 1
	v_add_f32_dpp v133, v133, v133 row_shr:8 row_mask:0xf bank_mask:0xf bound_ctrl:0
	s_nop 1
	v_readlane_b32 s35, v133, 15
	v_readlane_b32 s42, v133, 31
	v_readlane_b32 s43, v133, 47
	v_readlane_b32 s54, v133, 63
	v_mov_b32_e32 v135, s35
	v_add_f32_e32 v135, s42, v135
	v_add_f32_e32 v135, s43, v135
	v_add_f32_e32 v135, s54, v135
	v_mov_b32_e32 v136, 0x358637bd
	v_fmac_f32_e32 v136, 0x3a800000, v135
	v_rsq_f32_e32 v136, v136
	s_nop 0
	v_mul_f32_e32 v20, v20, v136
	v_mul_f32_e32 v20, v20, v52
	v_mul_f32_e32 v21, v21, v136
	v_mul_f32_e32 v21, v21, v53
	v_mul_f32_e32 v22, v22, v136
	v_mul_f32_e32 v22, v22, v54
	v_mul_f32_e32 v23, v23, v136
	v_mul_f32_e32 v23, v23, v55
	global_store_dwordx4 v132, v[20:23], s[48:49] offset:0
	v_mul_f32_e32 v24, v24, v136
	v_mul_f32_e32 v24, v24, v56
	v_mul_f32_e32 v25, v25, v136
	v_mul_f32_e32 v25, v25, v57
	v_mul_f32_e32 v26, v26, v136
	v_mul_f32_e32 v26, v26, v58
	v_mul_f32_e32 v27, v27, v136
	v_mul_f32_e32 v27, v27, v59
	global_store_dwordx4 v132, v[24:27], s[48:49] offset:1024
	v_mul_f32_e32 v28, v28, v136
	v_mul_f32_e32 v28, v28, v60
	v_mul_f32_e32 v29, v29, v136
	v_mul_f32_e32 v29, v29, v61
	v_mul_f32_e32 v30, v30, v136
	v_mul_f32_e32 v30, v30, v62
	v_mul_f32_e32 v31, v31, v136
	v_mul_f32_e32 v31, v31, v63
	global_store_dwordx4 v132, v[28:31], s[48:49] offset:2048
	v_mul_f32_e32 v32, v32, v136
	v_mul_f32_e32 v32, v32, v64
	v_mul_f32_e32 v33, v33, v136
	v_mul_f32_e32 v33, v33, v65
	v_mul_f32_e32 v34, v34, v136
	v_mul_f32_e32 v34, v34, v66
	v_mul_f32_e32 v35, v35, v136
	v_mul_f32_e32 v35, v35, v67
	global_store_dwordx4 v132, v[32:35], s[48:49] offset:3072
	s_add_u32 s48, s48, 0x800000
	s_addc_u32 s49, s49, 0
	s_waitcnt vmcnt(4)
	v_mul_f32_e32 v133, v36, v36
	v_fmac_f32_e32 v133, v37, v37
	v_fmac_f32_e32 v133, v38, v38
	v_fmac_f32_e32 v133, v39, v39
	v_fmac_f32_e32 v133, v40, v40
	v_fmac_f32_e32 v133, v41, v41
	v_fmac_f32_e32 v133, v42, v42
	v_fmac_f32_e32 v133, v43, v43
	v_fmac_f32_e32 v133, v44, v44
	v_fmac_f32_e32 v133, v45, v45
	v_fmac_f32_e32 v133, v46, v46
	v_fmac_f32_e32 v133, v47, v47
	v_fmac_f32_e32 v133, v48, v48
	v_fmac_f32_e32 v133, v49, v49
	v_fmac_f32_e32 v133, v50, v50
	v_fmac_f32_e32 v133, v51, v51
	s_nop 1
	v_add_f32_dpp v133, v133, v133 row_shr:1 row_mask:0xf bank_mask:0xf bound_ctrl:0
	s_nop 1
	v_add_f32_dpp v133, v133, v133 row_shr:2 row_mask:0xf bank_mask:0xf bound_ctrl:0
	s_nop 1
	v_add_f32_dpp v133, v133, v133 row_shr:4 row_mask:0xf bank_mask:0xf bound_ctrl:0
	s_nop 1
	v_add_f32_dpp v133, v133, v133 row_shr:8 row_mask:0xf bank_mask:0xf bound_ctrl:0
	s_nop 1
	v_readlane_b32 s35, v133, 15
	v_readlane_b32 s42, v133, 31
	v_readlane_b32 s43, v133, 47
	v_readlane_b32 s54, v133, 63
	v_mov_b32_e32 v135, s35
	v_add_f32_e32 v135, s42, v135
	v_add_f32_e32 v135, s43, v135
	v_add_f32_e32 v135, s54, v135
	v_mov_b32_e32 v136, 0x358637bd
	v_fmac_f32_e32 v136, 0x3a800000, v135
	v_rsq_f32_e32 v136, v136
	s_nop 0
	v_mul_f32_e32 v36, v36, v136
	v_mul_f32_e32 v36, v36, v52
	v_mul_f32_e32 v37, v37, v136
	v_mul_f32_e32 v37, v37, v53
	v_mul_f32_e32 v38, v38, v136
	v_mul_f32_e32 v38, v38, v54
	v_mul_f32_e32 v39, v39, v136
	v_mul_f32_e32 v39, v39, v55
	global_store_dwordx4 v132, v[36:39], s[48:49] offset:0
	v_mul_f32_e32 v40, v40, v136
	v_mul_f32_e32 v40, v40, v56
	v_mul_f32_e32 v41, v41, v136
	v_mul_f32_e32 v41, v41, v57
	v_mul_f32_e32 v42, v42, v136
	v_mul_f32_e32 v42, v42, v58
	v_mul_f32_e32 v43, v43, v136
	v_mul_f32_e32 v43, v43, v59
	global_store_dwordx4 v132, v[40:43], s[48:49] offset:1024
	v_mul_f32_e32 v44, v44, v136
	v_mul_f32_e32 v44, v44, v60
	v_mul_f32_e32 v45, v45, v136
	v_mul_f32_e32 v45, v45, v61
	v_mul_f32_e32 v46, v46, v136
	v_mul_f32_e32 v46, v46, v62
	v_mul_f32_e32 v47, v47, v136
	v_mul_f32_e32 v47, v47, v63
	global_store_dwordx4 v132, v[44:47], s[48:49] offset:2048
	v_mul_f32_e32 v48, v48, v136
	v_mul_f32_e32 v48, v48, v64
	v_mul_f32_e32 v49, v49, v136
	v_mul_f32_e32 v49, v49, v65
	v_mul_f32_e32 v50, v50, v136
	v_mul_f32_e32 v50, v50, v66
	v_mul_f32_e32 v51, v51, v136
	v_mul_f32_e32 v51, v51, v67
	global_store_dwordx4 v132, v[48:51], s[48:49] offset:3072
	s_waitcnt vmcnt(0)
	s_branch .LBB0_30

.LBB0_786:
	s_andn2_b64 vcc, exec, s[30:31]
	s_cbranch_vccnz .LBB0_768
	v_mov_b32_e32 v3, v206
	v_lshlrev_b32_e32 v4, 2, v3
	s_mov_b64 s[30:31], exec
	v_add_u32_e32 v5, 0x1000, v4
	global_load_dword v20, v4, s[80:81]
	global_load_dword v21, v4, s[80:81] offset:2048
	global_load_dword v22, v4, s[78:79]
	global_load_dword v23, v4, s[78:79] offset:2048
	global_load_dword v24, v5, s[78:79]
	global_load_dword v25, v5, s[78:79] offset:2048
	s_waitcnt vmcnt(0)
	v_mul_f32_e32 v26, 0xbfb8aa3b, v20
	v_mul_f32_e32 v27, 0xbfb8aa3b, v21
	v_mul_f32_e32 v28, 0xbfb8aa3b, v22
	v_mul_f32_e32 v29, 0xbfb8aa3b, v23
	v_mul_f32_e32 v30, 0xbfb8aa3b, v24
	v_mul_f32_e32 v31, 0xbfb8aa3b, v25
	v_exp_f32_e32 v26, v26
	v_exp_f32_e32 v27, v27
	v_exp_f32_e32 v28, v28
	v_exp_f32_e32 v29, v29
	v_exp_f32_e32 v30, v30
	v_exp_f32_e32 v31, v31
	s_nop 0
	v_add_f32_e32 v26, 1.0, v26
	v_add_f32_e32 v27, 1.0, v27
	v_add_f32_e32 v28, 1.0, v28
	v_add_f32_e32 v29, 1.0, v29
	v_add_f32_e32 v30, 1.0, v30
	v_add_f32_e32 v31, 1.0, v31
	v_div_scale_f32 v32, s[38:39], v26, v26, v20
	v_rcp_f32_e32 v33, v32
	s_nop 0
	v_fma_f32 v34, -v32, v33, 1.0
	v_fmac_f32_e32 v33, v34, v33
	v_div_scale_f32 v34, vcc, v20, v26, v20
	v_mul_f32_e32 v35, v34, v33
	v_fma_f32 v36, -v32, v35, v34
	v_fmac_f32_e32 v35, v36, v33
	v_fma_f32 v32, -v32, v35, v34
	v_div_fmas_f32 v32, v32, v33, v35
	v_div_fixup_f32 v20, v32, v26, v20
	ds_write_b32 v4, v20
	v_div_scale_f32 v32, s[38:39], v27, v27, v21
	v_rcp_f32_e32 v33, v32
	s_nop 0
	v_fma_f32 v34, -v32, v33, 1.0
	v_fmac_f32_e32 v33, v34, v33
	v_div_scale_f32 v34, vcc, v21, v27, v21
	v_mul_f32_e32 v35, v34, v33
	v_fma_f32 v36, -v32, v35, v34
	v_fmac_f32_e32 v35, v36, v33
	v_fma_f32 v32, -v32, v35, v34
	v_div_fmas_f32 v32, v32, v33, v35
	v_div_fixup_f32 v21, v32, v27, v21
	ds_write_b32 v4, v21 offset:2048
	v_div_scale_f32 v32, s[38:39], v28, v28, v22
	v_rcp_f32_e32 v33, v32
	s_nop 0
	v_fma_f32 v34, -v32, v33, 1.0
	v_fmac_f32_e32 v33, v34, v33
	v_div_scale_f32 v34, vcc, v22, v28, v22
	v_mul_f32_e32 v35, v34, v33
	v_fma_f32 v36, -v32, v35, v34
	v_fmac_f32_e32 v35, v36, v33
	v_fma_f32 v32, -v32, v35, v34
	v_div_fmas_f32 v32, v32, v33, v35
	v_div_fixup_f32 v22, v32, v28, v22
	ds_write_b32 v4, v22 offset:4096
	v_div_scale_f32 v32, s[38:39], v29, v29, v23
	v_rcp_f32_e32 v33, v32
	s_nop 0
	v_fma_f32 v34, -v32, v33, 1.0
	v_fmac_f32_e32 v33, v34, v33
	v_div_scale_f32 v34, vcc, v23, v29, v23
	v_mul_f32_e32 v35, v34, v33
	v_fma_f32 v36, -v32, v35, v34
	v_fmac_f32_e32 v35, v36, v33
	v_fma_f32 v32, -v32, v35, v34
	v_div_fmas_f32 v32, v32, v33, v35
	v_div_fixup_f32 v23, v32, v29, v23
	ds_write_b32 v4, v23 offset:6144
	v_div_scale_f32 v32, s[38:39], v30, v30, v24
	v_rcp_f32_e32 v33, v32
	s_nop 0
	v_fma_f32 v34, -v32, v33, 1.0
	v_fmac_f32_e32 v33, v34, v33
	v_div_scale_f32 v34, vcc, v24, v30, v24
	v_mul_f32_e32 v35, v34, v33
	v_fma_f32 v36, -v32, v35, v34
	v_fmac_f32_e32 v35, v36, v33
	v_fma_f32 v32, -v32, v35, v34
	v_div_fmas_f32 v32, v32, v33, v35
	v_div_fixup_f32 v24, v32, v30, v24
	ds_write_b32 v4, v24 offset:8192
	v_div_scale_f32 v32, s[38:39], v31, v31, v25
	v_rcp_f32_e32 v33, v32
	s_nop 0
	v_fma_f32 v34, -v32, v33, 1.0
	v_fmac_f32_e32 v33, v34, v33
	v_div_scale_f32 v34, vcc, v25, v31, v25
	v_mul_f32_e32 v35, v34, v33
	v_fma_f32 v36, -v32, v35, v34
	v_fmac_f32_e32 v35, v36, v33
	v_fma_f32 v32, -v32, v35, v34
	v_div_fmas_f32 v32, v32, v33, v35
	v_div_fixup_f32 v25, v32, v31, v25
	ds_write_b32 v4, v25 offset:10240

.LBB0_798:
	s_mov_b32 s37, 0
	global_load_dwordx4 v[20:23], v[0:1], off
	s_mov_b32 s36, 0x6000
	v_lshl_add_u64 v[148:149], v[0:1], 0, s[36:37]
	global_load_dwordx4 v[24:27], v[148:149], off
	s_mov_b32 s36, 0xc000
	v_lshl_add_u64 v[148:149], v[0:1], 0, s[36:37]
	global_load_dwordx4 v[28:31], v[148:149], off
	s_mov_b32 s36, 0x12000
	v_lshl_add_u64 v[148:149], v[0:1], 0, s[36:37]
	global_load_dwordx4 v[32:35], v[148:149], off
	s_mov_b32 s36, 0x18000
	v_lshl_add_u64 v[148:149], v[0:1], 0, s[36:37]
	global_load_dwordx4 v[36:39], v[148:149], off
	s_mov_b32 s36, 0x1e000
	v_lshl_add_u64 v[148:149], v[0:1], 0, s[36:37]
	global_load_dwordx4 v[40:43], v[148:149], off
	s_mov_b32 s36, 0x24000
	v_lshl_add_u64 v[148:149], v[0:1], 0, s[36:37]
	global_load_dwordx4 v[44:47], v[148:149], off
	s_mov_b32 s36, 0x2a000
	v_lshl_add_u64 v[148:149], v[0:1], 0, s[36:37]
	global_load_dwordx4 v[48:51], v[148:149], off
	s_mov_b32 s36, 0x30000
	v_lshl_add_u64 v[148:149], v[0:1], 0, s[36:37]
	global_load_dwordx4 v[52:55], v[148:149], off
	s_mov_b32 s36, 0x36000
	v_lshl_add_u64 v[148:149], v[0:1], 0, s[36:37]
	global_load_dwordx4 v[56:59], v[148:149], off
	s_mov_b32 s36, 0x3c000
	v_lshl_add_u64 v[148:149], v[0:1], 0, s[36:37]
	global_load_dwordx4 v[60:63], v[148:149], off
	s_mov_b32 s36, 0x42000
	v_lshl_add_u64 v[148:149], v[0:1], 0, s[36:37]
	global_load_dwordx4 v[64:67], v[148:149], off
	s_mov_b32 s36, 0x48000
	v_lshl_add_u64 v[148:149], v[0:1], 0, s[36:37]
	global_load_dwordx4 v[68:71], v[148:149], off
	s_mov_b32 s36, 0x4e000
	v_lshl_add_u64 v[148:149], v[0:1], 0, s[36:37]
	global_load_dwordx4 v[72:75], v[148:149], off
	s_mov_b32 s36, 0x54000
	v_lshl_add_u64 v[148:149], v[0:1], 0, s[36:37]
	global_load_dwordx4 v[76:79], v[148:149], off
	s_mov_b32 s36, 0x5a000
	v_lshl_add_u64 v[148:149], v[0:1], 0, s[36:37]
	global_load_dwordx4 v[80:83], v[148:149], off
	s_mov_b32 s36, 0x60000
	v_lshl_add_u64 v[148:149], v[0:1], 0, s[36:37]
	global_load_dwordx4 v[84:87], v[148:149], off
	s_mov_b32 s36, 0x66000
	v_lshl_add_u64 v[148:149], v[0:1], 0, s[36:37]
	global_load_dwordx4 v[88:91], v[148:149], off
	s_mov_b32 s36, 0x6c000
	v_lshl_add_u64 v[148:149], v[0:1], 0, s[36:37]
	global_load_dwordx4 v[92:95], v[148:149], off
	s_mov_b32 s36, 0x72000
	v_lshl_add_u64 v[148:149], v[0:1], 0, s[36:37]
	global_load_dwordx4 v[96:99], v[148:149], off
	s_mov_b32 s36, 0x78000
	v_lshl_add_u64 v[148:149], v[0:1], 0, s[36:37]
	global_load_dwordx4 v[100:103], v[148:149], off
	s_mov_b32 s36, 0x7e000
	v_lshl_add_u64 v[148:149], v[0:1], 0, s[36:37]
	global_load_dwordx4 v[104:107], v[148:149], off
	s_mov_b32 s36, 0x84000
	v_lshl_add_u64 v[148:149], v[0:1], 0, s[36:37]
	global_load_dwordx4 v[108:111], v[148:149], off
	s_mov_b32 s36, 0x8a000
	v_lshl_add_u64 v[148:149], v[0:1], 0, s[36:37]
	global_load_dwordx4 v[112:115], v[148:149], off
	s_mov_b32 s36, 0x90000
	v_lshl_add_u64 v[148:149], v[0:1], 0, s[36:37]
	global_load_dwordx4 v[116:119], v[148:149], off
	s_mov_b32 s36, 0x96000
	v_lshl_add_u64 v[148:149], v[0:1], 0, s[36:37]
	global_load_dwordx4 v[120:123], v[148:149], off
	s_mov_b32 s36, 0x9c000
	v_lshl_add_u64 v[148:149], v[0:1], 0, s[36:37]
	global_load_dwordx4 v[124:127], v[148:149], off
	s_mov_b32 s36, 0xa2000
	v_lshl_add_u64 v[148:149], v[0:1], 0, s[36:37]
	global_load_dwordx4 v[128:131], v[148:149], off
	s_mov_b32 s36, 0xa8000
	v_lshl_add_u64 v[148:149], v[0:1], 0, s[36:37]
	global_load_dwordx4 v[132:135], v[148:149], off
	s_mov_b32 s36, 0xae000
	v_lshl_add_u64 v[148:149], v[0:1], 0, s[36:37]
	global_load_dwordx4 v[136:139], v[148:149], off
	s_mov_b32 s36, 0xb4000
	v_lshl_add_u64 v[148:149], v[0:1], 0, s[36:37]
	global_load_dwordx4 v[140:143], v[148:149], off
	s_mov_b32 s36, 0xba000
	v_lshl_add_u64 v[148:149], v[0:1], 0, s[36:37]
	global_load_dwordx4 v[144:147], v[148:149], off
	ds_read_b128 v[150:153], v18 offset:0
	ds_read_b128 v[154:157], v18 offset:16
	ds_read_b128 v[158:161], v18 offset:4096
	ds_read_b128 v[162:165], v18 offset:4112
	ds_read_b128 v[166:169], v18 offset:8192
	ds_read_b128 v[170:173], v18 offset:8208
	s_waitcnt vmcnt(24) lgkmcnt(0)
	v_fmac_f32_e32 v4, v150, v20
	v_fmac_f32_e32 v5, v150, v21
	v_fmac_f32_e32 v6, v150, v22
	v_fmac_f32_e32 v7, v150, v23
	v_fmac_f32_e32 v12, v158, v20
	v_fmac_f32_e32 v13, v158, v21
	v_fmac_f32_e32 v14, v158, v22
	v_fmac_f32_e32 v15, v158, v23
	v_fmac_f32_e32 v8, v166, v20
	v_fmac_f32_e32 v9, v166, v21
	v_fmac_f32_e32 v10, v166, v22
	v_fmac_f32_e32 v11, v166, v23
	v_fmac_f32_e32 v4, v151, v24
	v_fmac_f32_e32 v5, v151, v25
	v_fmac_f32_e32 v6, v151, v26
	v_fmac_f32_e32 v7, v151, v27
	v_fmac_f32_e32 v12, v159, v24
	v_fmac_f32_e32 v13, v159, v25
	v_fmac_f32_e32 v14, v159, v26
	v_fmac_f32_e32 v15, v159, v27
	v_fmac_f32_e32 v8, v167, v24
	v_fmac_f32_e32 v9, v167, v25
	v_fmac_f32_e32 v10, v167, v26
	v_fmac_f32_e32 v11, v167, v27
	v_fmac_f32_e32 v4, v152, v28
	v_fmac_f32_e32 v5, v152, v29
	v_fmac_f32_e32 v6, v152, v30
	v_fmac_f32_e32 v7, v152, v31
	v_fmac_f32_e32 v12, v160, v28
	v_fmac_f32_e32 v13, v160, v29
	v_fmac_f32_e32 v14, v160, v30
	v_fmac_f32_e32 v15, v160, v31
	v_fmac_f32_e32 v8, v168, v28
	v_fmac_f32_e32 v9, v168, v29
	v_fmac_f32_e32 v10, v168, v30
	v_fmac_f32_e32 v11, v168, v31
	v_fmac_f32_e32 v4, v153, v32
	v_fmac_f32_e32 v5, v153, v33
	v_fmac_f32_e32 v6, v153, v34
	v_fmac_f32_e32 v7, v153, v35
	v_fmac_f32_e32 v12, v161, v32
	v_fmac_f32_e32 v13, v161, v33
	v_fmac_f32_e32 v14, v161, v34
	v_fmac_f32_e32 v15, v161, v35
	v_fmac_f32_e32 v8, v169, v32
	v_fmac_f32_e32 v9, v169, v33
	v_fmac_f32_e32 v10, v169, v34
	v_fmac_f32_e32 v11, v169, v35
	v_fmac_f32_e32 v4, v154, v36
	v_fmac_f32_e32 v5, v154, v37
	v_fmac_f32_e32 v6, v154, v38
	v_fmac_f32_e32 v7, v154, v39
	v_fmac_f32_e32 v12, v162, v36
	v_fmac_f32_e32 v13, v162, v37
	v_fmac_f32_e32 v14, v162, v38
	v_fmac_f32_e32 v15, v162, v39
	v_fmac_f32_e32 v8, v170, v36
	v_fmac_f32_e32 v9, v170, v37
	v_fmac_f32_e32 v10, v170, v38
	v_fmac_f32_e32 v11, v170, v39
	v_fmac_f32_e32 v4, v155, v40
	v_fmac_f32_e32 v5, v155, v41
	v_fmac_f32_e32 v6, v155, v42
	v_fmac_f32_e32 v7, v155, v43
	v_fmac_f32_e32 v12, v163, v40
	v_fmac_f32_e32 v13, v163, v41
	v_fmac_f32_e32 v14, v163, v42
	v_fmac_f32_e32 v15, v163, v43
	v_fmac_f32_e32 v8, v171, v40
	v_fmac_f32_e32 v9, v171, v41
	v_fmac_f32_e32 v10, v171, v42
	v_fmac_f32_e32 v11, v171, v43
	v_fmac_f32_e32 v4, v156, v44
	v_fmac_f32_e32 v5, v156, v45
	v_fmac_f32_e32 v6, v156, v46
	v_fmac_f32_e32 v7, v156, v47
	v_fmac_f32_e32 v12, v164, v44
	v_fmac_f32_e32 v13, v164, v45
	v_fmac_f32_e32 v14, v164, v46
	v_fmac_f32_e32 v15, v164, v47
	v_fmac_f32_e32 v8, v172, v44
	v_fmac_f32_e32 v9, v172, v45
	v_fmac_f32_e32 v10, v172, v46
	v_fmac_f32_e32 v11, v172, v47
	v_fmac_f32_e32 v4, v157, v48
	v_fmac_f32_e32 v5, v157, v49
	v_fmac_f32_e32 v6, v157, v50
	v_fmac_f32_e32 v7, v157, v51
	v_fmac_f32_e32 v12, v165, v48
	v_fmac_f32_e32 v13, v165, v49
	v_fmac_f32_e32 v14, v165, v50
	v_fmac_f32_e32 v15, v165, v51
	v_fmac_f32_e32 v8, v173, v48
	v_fmac_f32_e32 v9, v173, v49
	v_fmac_f32_e32 v10, v173, v50
	v_fmac_f32_e32 v11, v173, v51
	ds_read_b128 v[150:153], v18 offset:32
	ds_read_b128 v[154:157], v18 offset:48
	ds_read_b128 v[158:161], v18 offset:4128
	ds_read_b128 v[162:165], v18 offset:4144
	ds_read_b128 v[166:169], v18 offset:8224
	ds_read_b128 v[170:173], v18 offset:8240
	s_waitcnt vmcnt(16) lgkmcnt(0)
	v_fmac_f32_e32 v4, v150, v52
	v_fmac_f32_e32 v5, v150, v53
	v_fmac_f32_e32 v6, v150, v54
	v_fmac_f32_e32 v7, v150, v55
	v_fmac_f32_e32 v12, v158, v52
	v_fmac_f32_e32 v13, v158, v53
	v_fmac_f32_e32 v14, v158, v54
	v_fmac_f32_e32 v15, v158, v55
	v_fmac_f32_e32 v8, v166, v52
	v_fmac_f32_e32 v9, v166, v53
	v_fmac_f32_e32 v10, v166, v54
	v_fmac_f32_e32 v11, v166, v55
	v_fmac_f32_e32 v4, v151, v56
	v_fmac_f32_e32 v5, v151, v57
	v_fmac_f32_e32 v6, v151, v58
	v_fmac_f32_e32 v7, v151, v59
	v_fmac_f32_e32 v12, v159, v56
	v_fmac_f32_e32 v13, v159, v57
	v_fmac_f32_e32 v14, v159, v58
	v_fmac_f32_e32 v15, v159, v59
	v_fmac_f32_e32 v8, v167, v56
	v_fmac_f32_e32 v9, v167, v57
	v_fmac_f32_e32 v10, v167, v58
	v_fmac_f32_e32 v11, v167, v59
	v_fmac_f32_e32 v4, v152, v60
	v_fmac_f32_e32 v5, v152, v61
	v_fmac_f32_e32 v6, v152, v62
	v_fmac_f32_e32 v7, v152, v63
	v_fmac_f32_e32 v12, v160, v60
	v_fmac_f32_e32 v13, v160, v61
	v_fmac_f32_e32 v14, v160, v62
	v_fmac_f32_e32 v15, v160, v63
	v_fmac_f32_e32 v8, v168, v60
	v_fmac_f32_e32 v9, v168, v61
	v_fmac_f32_e32 v10, v168, v62
	v_fmac_f32_e32 v11, v168, v63
	v_fmac_f32_e32 v4, v153, v64
	v_fmac_f32_e32 v5, v153, v65
	v_fmac_f32_e32 v6, v153, v66
	v_fmac_f32_e32 v7, v153, v67
	v_fmac_f32_e32 v12, v161, v64
	v_fmac_f32_e32 v13, v161, v65
	v_fmac_f32_e32 v14, v161, v66
	v_fmac_f32_e32 v15, v161, v67
	v_fmac_f32_e32 v8, v169, v64
	v_fmac_f32_e32 v9, v169, v65
	v_fmac_f32_e32 v10, v169, v66
	v_fmac_f32_e32 v11, v169, v67
	v_fmac_f32_e32 v4, v154, v68
	v_fmac_f32_e32 v5, v154, v69
	v_fmac_f32_e32 v6, v154, v70
	v_fmac_f32_e32 v7, v154, v71
	v_fmac_f32_e32 v12, v162, v68
	v_fmac_f32_e32 v13, v162, v69
	v_fmac_f32_e32 v14, v162, v70
	v_fmac_f32_e32 v15, v162, v71
	v_fmac_f32_e32 v8, v170, v68
	v_fmac_f32_e32 v9, v170, v69
	v_fmac_f32_e32 v10, v170, v70
	v_fmac_f32_e32 v11, v170, v71
	v_fmac_f32_e32 v4, v155, v72
	v_fmac_f32_e32 v5, v155, v73
	v_fmac_f32_e32 v6, v155, v74
	v_fmac_f32_e32 v7, v155, v75
	v_fmac_f32_e32 v12, v163, v72
	v_fmac_f32_e32 v13, v163, v73
	v_fmac_f32_e32 v14, v163, v74
	v_fmac_f32_e32 v15, v163, v75
	v_fmac_f32_e32 v8, v171, v72
	v_fmac_f32_e32 v9, v171, v73
	v_fmac_f32_e32 v10, v171, v74
	v_fmac_f32_e32 v11, v171, v75
	v_fmac_f32_e32 v4, v156, v76
	v_fmac_f32_e32 v5, v156, v77
	v_fmac_f32_e32 v6, v156, v78
	v_fmac_f32_e32 v7, v156, v79
	v_fmac_f32_e32 v12, v164, v76
	v_fmac_f32_e32 v13, v164, v77
	v_fmac_f32_e32 v14, v164, v78
	v_fmac_f32_e32 v15, v164, v79
	v_fmac_f32_e32 v8, v172, v76
	v_fmac_f32_e32 v9, v172, v77
	v_fmac_f32_e32 v10, v172, v78
	v_fmac_f32_e32 v11, v172, v79
	v_fmac_f32_e32 v4, v157, v80
	v_fmac_f32_e32 v5, v157, v81
	v_fmac_f32_e32 v6, v157, v82
	v_fmac_f32_e32 v7, v157, v83
	v_fmac_f32_e32 v12, v165, v80
	v_fmac_f32_e32 v13, v165, v81
	v_fmac_f32_e32 v14, v165, v82
	v_fmac_f32_e32 v15, v165, v83
	v_fmac_f32_e32 v8, v173, v80
	v_fmac_f32_e32 v9, v173, v81
	v_fmac_f32_e32 v10, v173, v82
	v_fmac_f32_e32 v11, v173, v83
	ds_read_b128 v[150:153], v18 offset:64
	ds_read_b128 v[154:157], v18 offset:80
	ds_read_b128 v[158:161], v18 offset:4160
	ds_read_b128 v[162:165], v18 offset:4176
	ds_read_b128 v[166:169], v18 offset:8256
	ds_read_b128 v[170:173], v18 offset:8272
	s_waitcnt vmcnt(8) lgkmcnt(0)
	v_fmac_f32_e32 v4, v150, v84
	v_fmac_f32_e32 v5, v150, v85
	v_fmac_f32_e32 v6, v150, v86
	v_fmac_f32_e32 v7, v150, v87
	v_fmac_f32_e32 v12, v158, v84
	v_fmac_f32_e32 v13, v158, v85
	v_fmac_f32_e32 v14, v158, v86
	v_fmac_f32_e32 v15, v158, v87
	v_fmac_f32_e32 v8, v166, v84
	v_fmac_f32_e32 v9, v166, v85
	v_fmac_f32_e32 v10, v166, v86
	v_fmac_f32_e32 v11, v166, v87
	v_fmac_f32_e32 v4, v151, v88
	v_fmac_f32_e32 v5, v151, v89
	v_fmac_f32_e32 v6, v151, v90
	v_fmac_f32_e32 v7, v151, v91
	v_fmac_f32_e32 v12, v159, v88
	v_fmac_f32_e32 v13, v159, v89
	v_fmac_f32_e32 v14, v159, v90
	v_fmac_f32_e32 v15, v159, v91
	v_fmac_f32_e32 v8, v167, v88
	v_fmac_f32_e32 v9, v167, v89
	v_fmac_f32_e32 v10, v167, v90
	v_fmac_f32_e32 v11, v167, v91
	v_fmac_f32_e32 v4, v152, v92
	v_fmac_f32_e32 v5, v152, v93
	v_fmac_f32_e32 v6, v152, v94
	v_fmac_f32_e32 v7, v152, v95
	v_fmac_f32_e32 v12, v160, v92
	v_fmac_f32_e32 v13, v160, v93
	v_fmac_f32_e32 v14, v160, v94
	v_fmac_f32_e32 v15, v160, v95
	v_fmac_f32_e32 v8, v168, v92
	v_fmac_f32_e32 v9, v168, v93
	v_fmac_f32_e32 v10, v168, v94
	v_fmac_f32_e32 v11, v168, v95
	v_fmac_f32_e32 v4, v153, v96
	v_fmac_f32_e32 v5, v153, v97
	v_fmac_f32_e32 v6, v153, v98
	v_fmac_f32_e32 v7, v153, v99
	v_fmac_f32_e32 v12, v161, v96
	v_fmac_f32_e32 v13, v161, v97
	v_fmac_f32_e32 v14, v161, v98
	v_fmac_f32_e32 v15, v161, v99
	v_fmac_f32_e32 v8, v169, v96
	v_fmac_f32_e32 v9, v169, v97
	v_fmac_f32_e32 v10, v169, v98
	v_fmac_f32_e32 v11, v169, v99
	v_fmac_f32_e32 v4, v154, v100
	v_fmac_f32_e32 v5, v154, v101
	v_fmac_f32_e32 v6, v154, v102
	v_fmac_f32_e32 v7, v154, v103
	v_fmac_f32_e32 v12, v162, v100
	v_fmac_f32_e32 v13, v162, v101
	v_fmac_f32_e32 v14, v162, v102
	v_fmac_f32_e32 v15, v162, v103
	v_fmac_f32_e32 v8, v170, v100
	v_fmac_f32_e32 v9, v170, v101
	v_fmac_f32_e32 v10, v170, v102
	v_fmac_f32_e32 v11, v170, v103
	v_fmac_f32_e32 v4, v155, v104
	v_fmac_f32_e32 v5, v155, v105
	v_fmac_f32_e32 v6, v155, v106
	v_fmac_f32_e32 v7, v155, v107
	v_fmac_f32_e32 v12, v163, v104
	v_fmac_f32_e32 v13, v163, v105
	v_fmac_f32_e32 v14, v163, v106
	v_fmac_f32_e32 v15, v163, v107
	v_fmac_f32_e32 v8, v171, v104
	v_fmac_f32_e32 v9, v171, v105
	v_fmac_f32_e32 v10, v171, v106
	v_fmac_f32_e32 v11, v171, v107
	v_fmac_f32_e32 v4, v156, v108
	v_fmac_f32_e32 v5, v156, v109
	v_fmac_f32_e32 v6, v156, v110
	v_fmac_f32_e32 v7, v156, v111
	v_fmac_f32_e32 v12, v164, v108
	v_fmac_f32_e32 v13, v164, v109
	v_fmac_f32_e32 v14, v164, v110
	v_fmac_f32_e32 v15, v164, v111
	v_fmac_f32_e32 v8, v172, v108
	v_fmac_f32_e32 v9, v172, v109
	v_fmac_f32_e32 v10, v172, v110
	v_fmac_f32_e32 v11, v172, v111
	v_fmac_f32_e32 v4, v157, v112
	v_fmac_f32_e32 v5, v157, v113
	v_fmac_f32_e32 v6, v157, v114
	v_fmac_f32_e32 v7, v157, v115
	v_fmac_f32_e32 v12, v165, v112
	v_fmac_f32_e32 v13, v165, v113
	v_fmac_f32_e32 v14, v165, v114
	v_fmac_f32_e32 v15, v165, v115
	v_fmac_f32_e32 v8, v173, v112
	v_fmac_f32_e32 v9, v173, v113
	v_fmac_f32_e32 v10, v173, v114
	v_fmac_f32_e32 v11, v173, v115
	ds_read_b128 v[150:153], v18 offset:96
	ds_read_b128 v[154:157], v18 offset:112
	ds_read_b128 v[158:161], v18 offset:4192
	ds_read_b128 v[162:165], v18 offset:4208
	ds_read_b128 v[166:169], v18 offset:8288
	ds_read_b128 v[170:173], v18 offset:8304
	s_waitcnt vmcnt(0) lgkmcnt(0)
	v_fmac_f32_e32 v4, v150, v116
	v_fmac_f32_e32 v5, v150, v117
	v_fmac_f32_e32 v6, v150, v118
	v_fmac_f32_e32 v7, v150, v119
	v_fmac_f32_e32 v12, v158, v116
	v_fmac_f32_e32 v13, v158, v117
	v_fmac_f32_e32 v14, v158, v118
	v_fmac_f32_e32 v15, v158, v119
	v_fmac_f32_e32 v8, v166, v116
	v_fmac_f32_e32 v9, v166, v117
	v_fmac_f32_e32 v10, v166, v118
	v_fmac_f32_e32 v11, v166, v119
	v_fmac_f32_e32 v4, v151, v120
	v_fmac_f32_e32 v5, v151, v121
	v_fmac_f32_e32 v6, v151, v122
	v_fmac_f32_e32 v7, v151, v123
	v_fmac_f32_e32 v12, v159, v120
	v_fmac_f32_e32 v13, v159, v121
	v_fmac_f32_e32 v14, v159, v122
	v_fmac_f32_e32 v15, v159, v123
	v_fmac_f32_e32 v8, v167, v120
	v_fmac_f32_e32 v9, v167, v121
	v_fmac_f32_e32 v10, v167, v122
	v_fmac_f32_e32 v11, v167, v123
	v_fmac_f32_e32 v4, v152, v124
	v_fmac_f32_e32 v5, v152, v125
	v_fmac_f32_e32 v6, v152, v126
	v_fmac_f32_e32 v7, v152, v127
	v_fmac_f32_e32 v12, v160, v124
	v_fmac_f32_e32 v13, v160, v125
	v_fmac_f32_e32 v14, v160, v126
	v_fmac_f32_e32 v15, v160, v127
	v_fmac_f32_e32 v8, v168, v124
	v_fmac_f32_e32 v9, v168, v125
	v_fmac_f32_e32 v10, v168, v126
	v_fmac_f32_e32 v11, v168, v127
	v_fmac_f32_e32 v4, v153, v128
	v_fmac_f32_e32 v5, v153, v129
	v_fmac_f32_e32 v6, v153, v130
	v_fmac_f32_e32 v7, v153, v131
	v_fmac_f32_e32 v12, v161, v128
	v_fmac_f32_e32 v13, v161, v129
	v_fmac_f32_e32 v14, v161, v130
	v_fmac_f32_e32 v15, v161, v131
	v_fmac_f32_e32 v8, v169, v128
	v_fmac_f32_e32 v9, v169, v129
	v_fmac_f32_e32 v10, v169, v130
	v_fmac_f32_e32 v11, v169, v131
	v_fmac_f32_e32 v4, v154, v132
	v_fmac_f32_e32 v5, v154, v133
	v_fmac_f32_e32 v6, v154, v134
	v_fmac_f32_e32 v7, v154, v135
	v_fmac_f32_e32 v12, v162, v132
	v_fmac_f32_e32 v13, v162, v133
	v_fmac_f32_e32 v14, v162, v134
	v_fmac_f32_e32 v15, v162, v135
	v_fmac_f32_e32 v8, v170, v132
	v_fmac_f32_e32 v9, v170, v133
	v_fmac_f32_e32 v10, v170, v134
	v_fmac_f32_e32 v11, v170, v135
	v_fmac_f32_e32 v4, v155, v136
	v_fmac_f32_e32 v5, v155, v137
	v_fmac_f32_e32 v6, v155, v138
	v_fmac_f32_e32 v7, v155, v139
	v_fmac_f32_e32 v12, v163, v136
	v_fmac_f32_e32 v13, v163, v137
	v_fmac_f32_e32 v14, v163, v138
	v_fmac_f32_e32 v15, v163, v139
	v_fmac_f32_e32 v8, v171, v136
	v_fmac_f32_e32 v9, v171, v137
	v_fmac_f32_e32 v10, v171, v138
	v_fmac_f32_e32 v11, v171, v139
	v_fmac_f32_e32 v4, v156, v140
	v_fmac_f32_e32 v5, v156, v141
	v_fmac_f32_e32 v6, v156, v142
	v_fmac_f32_e32 v7, v156, v143
	v_fmac_f32_e32 v12, v164, v140
	v_fmac_f32_e32 v13, v164, v141
	v_fmac_f32_e32 v14, v164, v142
	v_fmac_f32_e32 v15, v164, v143
	v_fmac_f32_e32 v8, v172, v140
	v_fmac_f32_e32 v9, v172, v141
	v_fmac_f32_e32 v10, v172, v142
	v_fmac_f32_e32 v11, v172, v143
	v_fmac_f32_e32 v4, v157, v144
	v_fmac_f32_e32 v5, v157, v145
	v_fmac_f32_e32 v6, v157, v146
	v_fmac_f32_e32 v7, v157, v147
	v_fmac_f32_e32 v12, v165, v144
	v_fmac_f32_e32 v13, v165, v145
	v_fmac_f32_e32 v14, v165, v146
	v_fmac_f32_e32 v15, v165, v147
	v_fmac_f32_e32 v8, v173, v144
	v_fmac_f32_e32 v9, v173, v145
	v_fmac_f32_e32 v10, v173, v146
	v_fmac_f32_e32 v11, v173, v147
	s_movk_i32 s31, 0x300
	v_mul_lo_u32 v0, v16, s31
	s_movk_i32 s31, 0xc0
	v_lshl_or_b32 v0, v17, 2, v0
	v_cmp_gt_i32_e32 vcc, s31, v3
	ds_write_b128 v0, v[4:7] offset:12288
	ds_write_b128 v0, v[12:15] offset:12544
	ds_write_b128 v0, v[8:11] offset:12800
	s_waitcnt lgkmcnt(0)
	s_barrier
	s_and_saveexec_b64 s[36:37], vcc
	s_cbranch_execz .LBB0_767
	s_mul_i32 s31, s38, 0x1800
	v_ashrrev_i32_e32 v0, 6, v3
	v_and_b32_e32 v3, 63, v3
	s_add_i32 s31, s31, s30
	v_or_b32_e32 v4, s31, v3
	v_readlane_b32 s4, v237, 9
	v_ashrrev_i32_e32 v5, 31, v4
	v_readlane_b32 s5, v237, 10
	v_readlane_b32 s6, v237, 11
	v_readlane_b32 s7, v237, 12
	v_lshl_add_u64 v[4:5], v[4:5], 2, s[4:5]
	global_load_dword v1, v[4:5], off
	v_lshlrev_b32_e32 v4, 8, v0
	v_lshl_or_b32 v6, v3, 2, v4
	ds_read2st64_b32 v[4:5], v6 offset0:48 offset1:51
	s_movk_i32 s4, 0x1800
	v_readlane_b32 s8, v237, 13
	v_readlane_b32 s9, v237, 14
	v_readlane_b32 s10, v237, 15
	v_readlane_b32 s11, v237, 16
	v_readlane_b32 s12, v237, 17
	v_readlane_b32 s13, v237, 18
	v_readlane_b32 s14, v237, 19
	v_readlane_b32 s15, v237, 20
	v_readlane_b32 s16, v237, 21
	v_readlane_b32 s17, v237, 22
	v_readlane_b32 s18, v237, 23
	v_readlane_b32 s19, v237, 24
	s_waitcnt vmcnt(0) lgkmcnt(0)
	v_add_f32_e32 v1, v1, v4
	v_add_f32_e32 v1, v1, v5
	ds_read2st64_b32 v[4:5], v6 offset0:54 offset1:57
	s_waitcnt lgkmcnt(0)
	v_add_f32_e32 v1, v1, v4
	v_add_f32_e32 v1, v1, v5
	ds_read2st64_b32 v[4:5], v6 offset0:60 offset1:63
	s_waitcnt lgkmcnt(0)
	v_add_f32_e32 v1, v1, v4
	v_add_f32_e32 v1, v1, v5
	ds_read2st64_b32 v[4:5], v6 offset0:66 offset1:69
	s_waitcnt lgkmcnt(0)
	v_add_f32_e32 v1, v1, v4
	v_add_f32_e32 v1, v1, v5
	ds_read2st64_b32 v[4:5], v6 offset0:72 offset1:75
	s_waitcnt lgkmcnt(0)
	v_add_f32_e32 v1, v1, v4
	v_add_f32_e32 v1, v1, v5
	ds_read2st64_b32 v[4:5], v6 offset0:78 offset1:81
	s_waitcnt lgkmcnt(0)
	v_add_f32_e32 v1, v1, v4
	v_add_f32_e32 v1, v1, v5
	ds_read2st64_b32 v[4:5], v6 offset0:84 offset1:87
	s_waitcnt lgkmcnt(0)
	v_add_f32_e32 v1, v1, v4
	v_add_f32_e32 v1, v1, v5
	ds_read2st64_b32 v[4:5], v6 offset0:90 offset1:93
	s_waitcnt lgkmcnt(0)
	v_add_f32_e32 v1, v1, v4
	v_add_f32_e32 v1, v1, v5
	ds_read2st64_b32 v[4:5], v6 offset0:96 offset1:99
	s_waitcnt lgkmcnt(0)
	v_add_f32_e32 v1, v1, v4
	v_add_f32_e32 v1, v1, v5
	ds_read2st64_b32 v[4:5], v6 offset0:102 offset1:105
	s_waitcnt lgkmcnt(0)
	v_add_f32_e32 v1, v1, v4
	v_add_f32_e32 v1, v1, v5
	ds_read2st64_b32 v[4:5], v6 offset0:108 offset1:111
	s_waitcnt lgkmcnt(0)
	v_add_f32_e32 v1, v1, v4
	v_add_f32_e32 v1, v1, v5
	ds_read2st64_b32 v[4:5], v6 offset0:114 offset1:117
	s_waitcnt lgkmcnt(0)
	v_add_f32_e32 v1, v1, v4
	v_add_f32_e32 v1, v1, v5
	ds_read2st64_b32 v[4:5], v6 offset0:120 offset1:123
	s_waitcnt lgkmcnt(0)
	v_add_f32_e32 v1, v1, v4
	v_add_f32_e32 v1, v1, v5
	ds_read2st64_b32 v[4:5], v6 offset0:126 offset1:129
	s_waitcnt lgkmcnt(0)
	v_add_f32_e32 v1, v1, v4
	v_add_f32_e32 v1, v1, v5
	ds_read2st64_b32 v[4:5], v6 offset0:132 offset1:135
	s_waitcnt lgkmcnt(0)
	v_add_f32_e32 v1, v1, v4
	v_add_f32_e32 v1, v1, v5
	ds_read2st64_b32 v[4:5], v6 offset0:138 offset1:141
	s_waitcnt lgkmcnt(0)
	v_add_f32_e32 v1, v1, v4
	v_add_f32_e32 v4, v1, v5
	v_mad_u64_u32 v[0:1], s[38:39], s38, 3, v[0:1]
	v_mul_lo_u32 v0, v0, s4
	v_add_u32_e32 v0, s30, v0
	v_or_b32_e32 v0, v0, v3
	v_readlane_b32 s4, v236, 3
	v_ashrrev_i32_e32 v1, 31, v0
	v_readlane_b32 s5, v236, 4
	s_nop 1
	v_lshl_add_u64 v[0:1], v[0:1], 2, s[4:5]
	global_store_dword v[0:1], v4, off
	s_branch .LBB0_767
